# attention items: one static s_setprio 1 for waves 4-7 (the second wave on each SIMD) at item entry
# baseline (speedup 1.0000x reference)
; DI int otid() { int t = threadIdx.x; asm volatile("" : "+v"(t)); return t; }
; DI void attn_item(const bf16_t* P, bf16_t* Y, const float* sinkp, const float* rope, unsigned char* lds, bool is_ctx, int b, int blk, int hp) {
;     bf16_t* Ks = (bf16_t*)lds;
;     const int tid = otid(), wave = tid >> 6, lane = tid & 63, fr = lane & 15, fq = lane >> 4;
;     const int kvh = hp >> 1, h = hp * 2 + (wave >> 2);
.LBB0_473:
	v_readfirstlane_b32 s4, v176
	s_nop 3
	s_lshr_b32 s4, s4, 8
	s_cmp_eq_u32 s4, 1
	s_cbranch_scc0 .Latt_prio_done
	s_setprio 1
